# v49 + norm1 phase: row loop software-pipelined (next row's x prefetched) and each wave takes 17 consecutive rows so the per-batch adaLN parameters stay in L1
# speedup vs baseline: 1.0209x; 1.0015x over previous
; #define ARGP(i) ka_ptr(ka, (i) * 8)
; __global__ void __launch_bounds__(NWAVES * 64, 2) fwd_kernel(Args args_unused) {
;     ...
;                 const int cb = r % 96, kc = r / 96, col = cb * 64 + lane, k0 = kc * 64;
;                 const float* cin = ARGP(I_C); const float* cc = ARGP(I_CCTX);
;                 for (int idx = lane; idx < 9 * 64; idx += 64) { const int bb = idx >> 6, kk = idx & 63; const float v = (bb < 8) ? cin[bb * DM + k0 + kk] : cc[k0 + kk]; scr[idx] = v / (1.0f + __expf(-v)); }
;                 asm volatile("s_waitcnt lgkmcnt(0)" ::: "memory");
.LBB0_100:
	s_mul_hi_i32 s12, s90, 0x2aaaaaab
	s_lshr_b32 s13, s12, 31
	s_ashr_i32 s60, s12, 4
	s_add_i32 s60, s60, s13
	s_load_dwordx2 s[12:13], s[96:97], 8
	s_waitcnt lgkmcnt(0)
	s_load_dwordx2 s[18:19], s[96:97], 24
	s_waitcnt lgkmcnt(0)
	s_lshl_b32 s34, s60, 6
	s_and_saveexec_b64 s[14:15], s[6:7]
	s_cbranch_execz .LBB0_105
	s_waitcnt lgkmcnt(0)
	v_or_b32_e32 v34, s34, v114
	v_ashrrev_i32_e32 v35, 31, v34
	v_lshlrev_b32_e32 v33, 2, v34
	v_lshl_add_u64 v[34:35], v[34:35], 2, s[18:19]
	global_load_dword v246, v33, s[12:13]
	v_add_u32_e32 v37, 0x1000, v33
	global_load_dword v247, v37, s[12:13]
	v_add_u32_e32 v37, 0x2000, v33
	global_load_dword v248, v37, s[12:13]
	v_add_u32_e32 v37, 0x3000, v33
	global_load_dword v249, v37, s[12:13]
	v_add_u32_e32 v37, 0x4000, v33
	global_load_dword v250, v37, s[12:13]
	v_add_u32_e32 v37, 0x5000, v33
	global_load_dword v251, v37, s[12:13]
	v_add_u32_e32 v37, 0x6000, v33
	global_load_dword v252, v37, s[12:13]
	v_add_u32_e32 v37, 0x7000, v33
	global_load_dword v253, v37, s[12:13]
	global_load_dword v254, v[34:35], off
	s_waitcnt vmcnt(8)
	v_mul_f32_e32 v36, 0xbfb8aa3b, v246
	v_exp_f32_e32 v36, v36
	s_nop 0
	v_add_f32_e32 v31, 1.0, v36
	v_div_scale_f32 v36, s[20:21], v31, v31, v246
	v_rcp_f32_e32 v38, v36
	v_div_scale_f32 v39, vcc, v246, v31, v246
	v_fma_f32 v40, -v36, v38, 1.0
	v_fmac_f32_e32 v38, v40, v38
	v_mul_f32_e32 v40, v39, v38
	v_fma_f32 v41, -v36, v40, v39
	v_fmac_f32_e32 v40, v41, v38
	v_fma_f32 v36, -v36, v40, v39
	v_div_fmas_f32 v36, v36, v38, v40
	v_div_fixup_f32 v31, v36, v31, v246
	ds_write_b32 v116, v31
	s_waitcnt vmcnt(7)
	v_mul_f32_e32 v36, 0xbfb8aa3b, v247
	v_exp_f32_e32 v36, v36
	s_nop 0
	v_add_f32_e32 v31, 1.0, v36
	v_div_scale_f32 v36, s[20:21], v31, v31, v247
	v_rcp_f32_e32 v38, v36
	v_div_scale_f32 v39, vcc, v247, v31, v247
	v_fma_f32 v40, -v36, v38, 1.0
	v_fmac_f32_e32 v38, v40, v38
	v_mul_f32_e32 v40, v39, v38
	v_fma_f32 v41, -v36, v40, v39
	v_fmac_f32_e32 v40, v41, v38
	v_fma_f32 v36, -v36, v40, v39
	v_div_fmas_f32 v36, v36, v38, v40
	v_div_fixup_f32 v31, v36, v31, v247
	ds_write_b32 v116, v31 offset:256
	s_waitcnt vmcnt(6)
	v_mul_f32_e32 v36, 0xbfb8aa3b, v248
	v_exp_f32_e32 v36, v36
	s_nop 0
	v_add_f32_e32 v31, 1.0, v36
	v_div_scale_f32 v36, s[20:21], v31, v31, v248
	v_rcp_f32_e32 v38, v36
	v_div_scale_f32 v39, vcc, v248, v31, v248
	v_fma_f32 v40, -v36, v38, 1.0
	v_fmac_f32_e32 v38, v40, v38
	v_mul_f32_e32 v40, v39, v38
	v_fma_f32 v41, -v36, v40, v39
	v_fmac_f32_e32 v40, v41, v38
	v_fma_f32 v36, -v36, v40, v39
	v_div_fmas_f32 v36, v36, v38, v40
	v_div_fixup_f32 v31, v36, v31, v248
	ds_write_b32 v116, v31 offset:512
	s_waitcnt vmcnt(5)
	v_mul_f32_e32 v36, 0xbfb8aa3b, v249
	v_exp_f32_e32 v36, v36
	s_nop 0
	v_add_f32_e32 v31, 1.0, v36
	v_div_scale_f32 v36, s[20:21], v31, v31, v249
	v_rcp_f32_e32 v38, v36
	v_div_scale_f32 v39, vcc, v249, v31, v249
	v_fma_f32 v40, -v36, v38, 1.0
	v_fmac_f32_e32 v38, v40, v38
	v_mul_f32_e32 v40, v39, v38
	v_fma_f32 v41, -v36, v40, v39
	v_fmac_f32_e32 v40, v41, v38
	v_fma_f32 v36, -v36, v40, v39
	v_div_fmas_f32 v36, v36, v38, v40
	v_div_fixup_f32 v31, v36, v31, v249
	ds_write_b32 v116, v31 offset:768
	s_waitcnt vmcnt(4)
	v_mul_f32_e32 v36, 0xbfb8aa3b, v250
	v_exp_f32_e32 v36, v36
	s_nop 0
	v_add_f32_e32 v31, 1.0, v36
	v_div_scale_f32 v36, s[20:21], v31, v31, v250
	v_rcp_f32_e32 v38, v36
	v_div_scale_f32 v39, vcc, v250, v31, v250
	v_fma_f32 v40, -v36, v38, 1.0
	v_fmac_f32_e32 v38, v40, v38
	v_mul_f32_e32 v40, v39, v38
	v_fma_f32 v41, -v36, v40, v39
	v_fmac_f32_e32 v40, v41, v38
	v_fma_f32 v36, -v36, v40, v39
	v_div_fmas_f32 v36, v36, v38, v40
	v_div_fixup_f32 v31, v36, v31, v250
	ds_write_b32 v116, v31 offset:1024
	s_waitcnt vmcnt(3)
	v_mul_f32_e32 v36, 0xbfb8aa3b, v251
	v_exp_f32_e32 v36, v36
	s_nop 0
	v_add_f32_e32 v31, 1.0, v36
	v_div_scale_f32 v36, s[20:21], v31, v31, v251
	v_rcp_f32_e32 v38, v36
	v_div_scale_f32 v39, vcc, v251, v31, v251
	v_fma_f32 v40, -v36, v38, 1.0
	v_fmac_f32_e32 v38, v40, v38
	v_mul_f32_e32 v40, v39, v38
	v_fma_f32 v41, -v36, v40, v39
	v_fmac_f32_e32 v40, v41, v38
	v_fma_f32 v36, -v36, v40, v39
	v_div_fmas_f32 v36, v36, v38, v40
	v_div_fixup_f32 v31, v36, v31, v251
	ds_write_b32 v116, v31 offset:1280
	s_waitcnt vmcnt(2)
	v_mul_f32_e32 v36, 0xbfb8aa3b, v252
	v_exp_f32_e32 v36, v36
	s_nop 0
	v_add_f32_e32 v31, 1.0, v36
	v_div_scale_f32 v36, s[20:21], v31, v31, v252
	v_rcp_f32_e32 v38, v36
	v_div_scale_f32 v39, vcc, v252, v31, v252
	v_fma_f32 v40, -v36, v38, 1.0
	v_fmac_f32_e32 v38, v40, v38
	v_mul_f32_e32 v40, v39, v38
	v_fma_f32 v41, -v36, v40, v39
	v_fmac_f32_e32 v40, v41, v38
	v_fma_f32 v36, -v36, v40, v39
	v_div_fmas_f32 v36, v36, v38, v40
	v_div_fixup_f32 v31, v36, v31, v252
	ds_write_b32 v116, v31 offset:1536
	s_waitcnt vmcnt(1)
	v_mul_f32_e32 v36, 0xbfb8aa3b, v253
	v_exp_f32_e32 v36, v36
	s_nop 0
	v_add_f32_e32 v31, 1.0, v36
	v_div_scale_f32 v36, s[20:21], v31, v31, v253
	v_rcp_f32_e32 v38, v36
	v_div_scale_f32 v39, vcc, v253, v31, v253
	v_fma_f32 v40, -v36, v38, 1.0
	v_fmac_f32_e32 v38, v40, v38
	v_mul_f32_e32 v40, v39, v38
	v_fma_f32 v41, -v36, v40, v39
	v_fmac_f32_e32 v40, v41, v38
	v_fma_f32 v36, -v36, v40, v39
	v_div_fmas_f32 v36, v36, v38, v40
	v_div_fixup_f32 v31, v36, v31, v253
	ds_write_b32 v116, v31 offset:1792
	s_waitcnt vmcnt(0)
	v_mul_f32_e32 v36, 0xbfb8aa3b, v254
	v_exp_f32_e32 v36, v36
	s_nop 0
	v_add_f32_e32 v31, 1.0, v36
	v_div_scale_f32 v36, s[20:21], v31, v31, v254
	v_rcp_f32_e32 v38, v36
	v_div_scale_f32 v39, vcc, v254, v31, v254
	v_fma_f32 v40, -v36, v38, 1.0
	v_fmac_f32_e32 v38, v40, v38
	v_mul_f32_e32 v40, v39, v38
	v_fma_f32 v41, -v36, v40, v39
	v_fmac_f32_e32 v40, v41, v38
	v_fma_f32 v36, -v36, v40, v39
	v_div_fmas_f32 v36, v36, v38, v40
	v_div_fixup_f32 v31, v36, v31, v254
	ds_write_b32 v116, v31 offset:2048

; __global__ void __launch_bounds__(NWAVES * 64, 2) fwd_kernel(Args args_unused) {
;     ...
;         { const int nrow = grouped ? (4 * SEQ + 4 * CTXL) : MT;
;           for (int r = gw; r < nrow; r += NGW) { const int mrow = (!grouped || r < 4 * SEQ) ? r : ML + (r - 4 * SEQ); P1_ROW(mrow); } }
.LBB0_170:
	s_cmp_lt_i32 s89, 2
	s_cselect_b64 s[10:11], -1, 0
	s_and_b64 s[0:1], s[10:11], s[20:21]
	s_andn2_b64 vcc, exec, s[0:1]
	s_cbranch_vccnz .LBB0_183
	v_mbcnt_lo_u32_b32 v128, -1, 0
	v_mbcnt_hi_u32_b32 v128, -1, v128
	s_load_dwordx2 s[12:13], s[96:97], 0xb0
	s_waitcnt lgkmcnt(0)
	s_load_dwordx2 s[4:5], s[96:97], 0
	s_waitcnt lgkmcnt(0)
	s_load_dwordx2 s[6:7], s[96:97], 16
	s_waitcnt lgkmcnt(0)
	s_movk_i32 s3, 0x4400
	s_and_b64 s[0:1], s[18:19], exec
	s_load_dwordx2 s[14:15], s[96:97], 48
	s_waitcnt lgkmcnt(0)
	s_mov_b32 s0, 0x8800
	s_cmp_ge_i32 s22, s0
	s_cbranch_scc1 .LBB0_178
	v_mbcnt_lo_u32_b32 v0, -1, 0
	v_mbcnt_hi_u32_b32 v0, -1, v0
	v_and_b32_e32 v1, 64, v0
	v_add_u32_e32 v1, 64, v1
	v_xor_b32_e32 v2, 1, v0
	v_cmp_lt_i32_e32 vcc, v2, v1
	v_lshlrev_b32_e32 v4, 2, v128
	v_ashrrev_i32_e32 v5, 31, v4
	v_cndmask_b32_e32 v2, v0, v2, vcc
	v_lshlrev_b32_e32 v6, 2, v2
	v_xor_b32_e32 v2, 2, v0
	v_cmp_lt_i32_e32 vcc, v2, v1
	s_mov_b64 s[16:17], 0x2000000
	s_mov_b32 s9, 0
	v_cndmask_b32_e32 v2, v0, v2, vcc
	v_lshlrev_b32_e32 v7, 2, v2
	v_xor_b32_e32 v2, 4, v0
	v_cmp_lt_i32_e32 vcc, v2, v1
	v_mov_b32_e32 v12, 0x358637bd
	s_mov_b32 s1, 0x800000
	v_cndmask_b32_e32 v2, v0, v2, vcc
	v_lshlrev_b32_e32 v8, 2, v2
	v_xor_b32_e32 v2, 8, v0
	v_cmp_lt_i32_e32 vcc, v2, v1
	s_movk_i32 s3, 0x1000
	s_add_i32 s37, s22, 1
	s_mul_i32 s37, s37, 17
	s_mul_i32 s23, s22, 17
	s_cmp_eq_u32 s24, 0x800
	s_cselect_b32 s32, 1, s24
	s_cselect_b32 s23, s23, s22
	s_cselect_b32 s0, s37, s0
	v_cndmask_b32_e32 v2, v0, v2, vcc
	v_lshlrev_b32_e32 v9, 2, v2
	v_xor_b32_e32 v2, 16, v0
	v_cmp_lt_i32_e32 vcc, v2, v1
	s_nop 1
	v_cndmask_b32_e32 v2, v0, v2, vcc
	v_lshlrev_b32_e32 v10, 2, v2
	v_xor_b32_e32 v2, 32, v0
	v_cmp_lt_i32_e32 vcc, v2, v1
	s_nop 1
	v_cndmask_b32_e32 v0, v0, v2, vcc
	v_lshlrev_b32_e32 v11, 2, v0
	v_lshl_add_u64 v[0:1], v[4:5], 1, s[12:13]
	v_lshl_add_u64 v[0:1], v[0:1], 0, s[16:17]
	v_lshl_add_u64 v[2:3], v[4:5], 2, s[14:15]
	v_lshlrev_b64 v[4:5], 2, v[4:5]
	s_mov_b64 s[14:15], 0x1000
	s_mov_b32 s36, s23
	s_mov_b32 s34, s36
	s_cmpk_gt_i32 s34, 0x7fff
	s_cselect_b32 s20, s6, s4
	s_cselect_b32 s21, s7, s5
	s_cselect_b32 s8, 0x8000, 0
	s_sub_i32 s8, s34, s8
	s_lshl_b64 s[38:39], s[8:9], 12
	s_add_u32 s20, s20, s38
	s_addc_u32 s21, s21, s39
	v_lshl_add_u64 v[120:121], s[20:21], 0, v[4:5]
	global_load_dwordx4 v[104:107], v[120:121], off nt
	global_load_dwordx4 v[108:111], v[120:121], off offset:1024 nt
	global_load_dwordx4 v[112:115], v[120:121], off offset:3072 nt
	global_load_dwordx4 v[116:119], v[120:121], off offset:2048 nt
; __global__ void __launch_bounds__(NWAVES * 64, 2) fwd_kernel(Args args_unused) {
;     ...
;         { const int nrow = grouped ? (4 * SEQ + 4 * CTXL) : MT;
;           for (int r = gw; r < nrow; r += NGW) { const int mrow = (!grouped || r < 4 * SEQ) ? r : ML + (r - 4 * SEQ); P1_ROW(mrow); } }
.Lp1_loop:
	s_mov_b32 s16, s34
	s_mov_b32 s17, 0
	s_min_i32 s8, s34, 0x8000
	s_ashr_i32 s8, s8, 12
	s_mul_hi_i32 s21, s8, 0x6000
	s_mulk_i32 s8, 0x6000
	s_add_u32 s20, s12, s8
	s_addc_u32 s21, s13, s21
	v_lshl_add_u64 v[54:55], s[20:21], 0, v[4:5]
	v_add_co_u32_e32 v30, vcc, s3, v54
	v_lshl_add_u64 v[56:57], v[54:55], 0, s[14:15]
	s_nop 0
	v_addc_co_u32_e32 v31, vcc, 0, v55, vcc
	global_load_dwordx4 v[30:33], v[30:31], off
	s_nop 0
	global_load_dwordx4 v[34:37], v[56:57], off offset:1024
	global_load_dwordx4 v[38:41], v[2:3], off offset:1024
	global_load_dwordx4 v[42:45], v[2:3], off
	global_load_dwordx4 v[46:49], v[54:55], off offset:1024
	global_load_dwordx4 v[50:53], v[54:55], off
	global_load_dwordx4 v[80:83], v[56:57], off offset:2048
	global_load_dwordx4 v[84:87], v[2:3], off offset:2048
	global_load_dwordx4 v[88:91], v[56:57], off offset:3072
	global_load_dwordx4 v[92:95], v[2:3], off offset:3072
	global_load_dwordx4 v[96:99], v[54:55], off offset:2048
	global_load_dwordx4 v[100:103], v[54:55], off offset:3072
	s_waitcnt vmcnt(12)
	v_mov_b32_e32 v14, v104
	v_mov_b32_e32 v15, v105
	v_mov_b32_e32 v16, v106
	v_mov_b32_e32 v17, v107
	v_mov_b32_e32 v18, v108
	v_mov_b32_e32 v19, v109
	v_mov_b32_e32 v20, v110
	v_mov_b32_e32 v21, v111
	v_mov_b32_e32 v22, v112
	v_mov_b32_e32 v23, v113
	v_mov_b32_e32 v24, v114
	v_mov_b32_e32 v25, v115
	v_mov_b32_e32 v26, v116
	v_mov_b32_e32 v27, v117
	v_mov_b32_e32 v28, v118
	v_mov_b32_e32 v29, v119
	s_mov_b32 s37, s23
	s_add_i32 s23, s23, s32
	s_cmp_ge_i32 s23, s0
	s_cselect_b32 s36, s37, s23
	s_cselect_b32 s40, 1, 0
	s_mov_b32 s34, s36
	s_cmpk_gt_i32 s34, 0x7fff
	s_cselect_b32 s20, s6, s4
	s_cselect_b32 s21, s7, s5
	s_cselect_b32 s8, 0x8000, 0
	s_sub_i32 s8, s34, s8
	s_lshl_b64 s[38:39], s[8:9], 12
	s_add_u32 s20, s20, s38
	s_addc_u32 s21, s21, s39
	v_lshl_add_u64 v[120:121], s[20:21], 0, v[4:5]
	global_load_dwordx4 v[104:107], v[120:121], off nt
	global_load_dwordx4 v[108:111], v[120:121], off offset:1024 nt
	global_load_dwordx4 v[112:115], v[120:121], off offset:3072 nt
	global_load_dwordx4 v[116:119], v[120:121], off offset:2048 nt
	s_lshl_b64 s[16:17], s[16:17], 11
	v_pk_mul_f32 v[58:59], v[16:17], v[16:17]
	v_pk_mul_f32 v[60:61], v[14:15], v[14:15]
	v_pk_mul_f32 v[62:63], v[20:21], v[20:21]
	v_pk_mul_f32 v[64:65], v[18:19], v[18:19]
	v_pk_mov_b32 v[70:71], v[60:61], v[58:59] op_sel:[1,0]
	v_mov_b32_e32 v61, v59
	v_pk_mov_b32 v[58:59], v[64:65], v[62:63] op_sel:[1,0]
	v_mov_b32_e32 v65, v63
	v_mul_f32_e32 v69, v23, v23
	v_mul_f32_e32 v66, v27, v27
	v_mul_f32_e32 v68, v29, v29
	v_pk_add_f32 v[60:61], v[70:71], v[60:61]
	v_pk_add_f32 v[58:59], v[58:59], v[64:65]
	v_mul_f32_e32 v13, v22, v22
	v_mul_f32_e32 v72, v24, v24
	v_mul_f32_e32 v73, v25, v25
	v_pk_fma_f32 v[62:63], v[26:27], v[26:27], v[66:67] op_sel_hi:[1,1,0]
	v_pk_fma_f32 v[66:67], v[28:29], v[28:29], v[68:69] op_sel_hi:[1,1,0]
	v_pk_add_f32 v[60:61], v[60:61], v[60:61] op_sel:[0,1] op_sel_hi:[1,0]
	v_pk_add_f32 v[58:59], v[58:59], v[58:59] op_sel:[0,1] op_sel_hi:[1,0]
	v_mov_b32_e32 v63, v72
	v_mov_b32_e32 v67, v73
	v_mov_b32_e32 v61, v13
	v_mov_b32_e32 v59, v69
	v_pk_add_f32 v[62:63], v[62:63], v[66:67]
	v_pk_add_f32 v[58:59], v[60:61], v[58:59]
	s_waitcnt vmcnt(15)
	v_pk_add_f32 v[32:33], v[32:33], 1.0 op_sel_hi:[1,0]
	v_pk_add_f32 v[58:59], v[58:59], v[62:63]
	v_pk_add_f32 v[30:31], v[30:31], 1.0 op_sel_hi:[1,0]
	v_add_f32_e32 v13, v58, v59
	ds_bpermute_b32 v58, v6, v13
	s_waitcnt vmcnt(14)
	v_pk_add_f32 v[36:37], v[36:37], 1.0 op_sel_hi:[1,0]
	v_pk_add_f32 v[34:35], v[34:35], 1.0 op_sel_hi:[1,0]
	s_waitcnt lgkmcnt(0)
	v_add_f32_e32 v13, v13, v58
	ds_bpermute_b32 v58, v7, v13
	s_waitcnt lgkmcnt(0)
	v_add_f32_e32 v13, v13, v58
	ds_bpermute_b32 v58, v8, v13
	s_waitcnt lgkmcnt(0)
	v_add_f32_e32 v13, v13, v58
	ds_bpermute_b32 v58, v9, v13
	s_waitcnt lgkmcnt(0)
	v_add_f32_e32 v13, v13, v58
	ds_bpermute_b32 v58, v10, v13
	s_waitcnt lgkmcnt(0)
	v_add_f32_e32 v13, v13, v58
	ds_bpermute_b32 v60, v11, v13
	v_lshl_add_u64 v[58:59], v[0:1], 0, s[16:17]
	s_waitcnt lgkmcnt(0)
	v_add_f32_e32 v13, v13, v60
	v_fmamk_f32 v13, v13, 0x3a800000, v12
	v_mul_f32_e32 v60, 0x4b800000, v13
	v_cmp_gt_f32_e32 vcc, s1, v13
	s_nop 1
	v_cndmask_b32_e32 v13, v13, v60, vcc
	v_rsq_f32_e32 v13, v13
	s_nop 0
	v_mul_f32_e32 v60, 0x45800000, v13
	v_cndmask_b32_e32 v60, v13, v60, vcc
	v_pk_mul_f32 v[16:17], v[60:61], v[16:17] op_sel_hi:[0,1]
	v_pk_mul_f32 v[14:15], v[60:61], v[14:15] op_sel_hi:[0,1]
	v_pk_mul_f32 v[20:21], v[60:61], v[20:21] op_sel_hi:[0,1]
	v_pk_mul_f32 v[18:19], v[60:61], v[18:19] op_sel_hi:[0,1]
	s_waitcnt vmcnt(12)
	v_pk_mul_f32 v[14:15], v[42:43], v[14:15]
	v_pk_mul_f32 v[16:17], v[44:45], v[16:17]
	v_pk_mul_f32 v[18:19], v[38:39], v[18:19]
	v_pk_mul_f32 v[20:21], v[40:41], v[20:21]
	s_waitcnt vmcnt(10)
	v_pk_fma_f32 v[16:17], v[32:33], v[16:17], v[52:53]
	v_pk_fma_f32 v[14:15], v[30:31], v[14:15], v[50:51]
	v_pk_fma_f32 v[20:21], v[36:37], v[20:21], v[48:49]
	v_pk_fma_f32 v[18:19], v[34:35], v[18:19], v[46:47]
	v_cvt_pk_bf16_f32 v14, v14, v15
	v_cvt_pk_bf16_f32 v15, v16, v17
	v_cvt_pk_bf16_f32 v16, v18, v19
	v_cvt_pk_bf16_f32 v17, v20, v21
	global_store_dwordx2 v[58:59], v[14:15], off sc1
	global_store_dwordx2 v[58:59], v[16:17], off offset:512 sc1
	v_pk_mul_f32 v[28:29], v[60:61], v[28:29] op_sel_hi:[0,1]
	v_pk_mul_f32 v[26:27], v[60:61], v[26:27] op_sel_hi:[0,1]
	v_pk_mul_f32 v[24:25], v[60:61], v[24:25] op_sel_hi:[0,1]
	v_pk_mul_f32 v[22:23], v[60:61], v[22:23] op_sel_hi:[0,1]
	s_waitcnt vmcnt(11)
	v_pk_add_f32 v[16:17], v[82:83], 1.0 op_sel_hi:[1,0]
	v_pk_add_f32 v[14:15], v[80:81], 1.0 op_sel_hi:[1,0]
	s_waitcnt vmcnt(10)
	v_pk_mul_f32 v[18:19], v[84:85], v[26:27]
	v_pk_mul_f32 v[20:21], v[86:87], v[28:29]
	s_waitcnt vmcnt(9)
	v_pk_add_f32 v[26:27], v[90:91], 1.0 op_sel_hi:[1,0]
	v_pk_add_f32 v[28:29], v[88:89], 1.0 op_sel_hi:[1,0]
	s_waitcnt vmcnt(8)
	v_pk_mul_f32 v[22:23], v[92:93], v[22:23]
	v_pk_mul_f32 v[24:25], v[94:95], v[24:25]
	s_waitcnt vmcnt(7)
	v_pk_fma_f32 v[16:17], v[16:17], v[20:21], v[98:99]
	v_pk_fma_f32 v[14:15], v[14:15], v[18:19], v[96:97]
	s_waitcnt vmcnt(6)
	v_pk_fma_f32 v[18:19], v[26:27], v[24:25], v[102:103]
	v_pk_fma_f32 v[20:21], v[28:29], v[22:23], v[100:101]
	v_cvt_pk_bf16_f32 v14, v14, v15
	v_cvt_pk_bf16_f32 v15, v16, v17
	v_cvt_pk_bf16_f32 v16, v20, v21
	v_cvt_pk_bf16_f32 v17, v18, v19
	global_store_dwordx2 v[58:59], v[14:15], off offset:1024 sc1
	global_store_dwordx2 v[58:59], v[16:17], off offset:1536 sc1
	s_cmp_lg_u32 s40, 0
	s_cbranch_scc0 .Lp1_loop
	s_waitcnt vmcnt(0)
